# lean MB=3 K-loop also for P6 (all three MB=3 loops lean) + mvcvt
# speedup vs baseline: 1.0029x; 1.0029x over previous
.LBB0_923:
	s_add_u32 s8, s8, 0x60080
	v_mov_b32_e32 v0, 0
	s_addc_u32 s9, s9, 0
	s_mov_b32 s82, -2
	s_mov_b64 s[52:53], s[28:29]
	v_mov_b32_e32 v1, v0
	v_mov_b32_e32 v2, v0
	v_mov_b32_e32 v3, v0
	v_mov_b32_e32 v4, v0
	v_mov_b32_e32 v5, v0
	v_mov_b32_e32 v6, v0
	v_mov_b32_e32 v7, v0
	v_mov_b32_e32 v16, v0
	v_mov_b32_e32 v17, v0
	v_mov_b32_e32 v18, v0
	v_mov_b32_e32 v19, v0
	v_mov_b32_e32 v24, v0
	v_mov_b32_e32 v25, v0
	v_mov_b32_e32 v26, v0
	v_mov_b32_e32 v27, v0
	v_mov_b32_e32 v20, v0
	v_mov_b32_e32 v21, v0
	v_mov_b32_e32 v22, v0
	v_mov_b32_e32 v23, v0
	v_mov_b32_e32 v40, v0
	v_mov_b32_e32 v41, v0
	v_mov_b32_e32 v42, v0
	v_mov_b32_e32 v43, v0
	v_mov_b32_e32 v8, v0
	v_mov_b32_e32 v9, v0
	v_mov_b32_e32 v10, v0
	v_mov_b32_e32 v11, v0
	v_mov_b32_e32 v12, v0
	v_mov_b32_e32 v13, v0
	v_mov_b32_e32 v14, v0
	v_mov_b32_e32 v15, v0
	v_mov_b32_e32 v32, v0
	v_mov_b32_e32 v33, v0
	v_mov_b32_e32 v34, v0
	v_mov_b32_e32 v35, v0
	v_mov_b32_e32 v28, v0
	v_mov_b32_e32 v29, v0
	v_mov_b32_e32 v30, v0
	v_mov_b32_e32 v31, v0
	v_mov_b32_e32 v48, v0
	v_mov_b32_e32 v49, v0
	v_mov_b32_e32 v50, v0
	v_mov_b32_e32 v51, v0
	v_mov_b32_e32 v44, v0
	v_mov_b32_e32 v45, v0
	v_mov_b32_e32 v46, v0
	v_mov_b32_e32 v47, v0
	v_mov_b32_e32 v36, v0
	v_mov_b32_e32 v37, v0
	v_mov_b32_e32 v38, v0
	v_mov_b32_e32 v39, v0
	v_mov_b32_e32 v56, v0
	v_mov_b32_e32 v57, v0
	v_mov_b32_e32 v58, v0
	v_mov_b32_e32 v59, v0
	v_mov_b32_e32 v52, v0
	v_mov_b32_e32 v53, v0
	v_mov_b32_e32 v54, v0
	v_mov_b32_e32 v55, v0
	v_mov_b32_e32 v72, v0
	v_mov_b32_e32 v73, v0
	v_mov_b32_e32 v74, v0
	v_mov_b32_e32 v75, v0
	v_mov_b32_e32 v68, v0
	v_mov_b32_e32 v69, v0
	v_mov_b32_e32 v70, v0
	v_mov_b32_e32 v71, v0
	v_mov_b32_e32 v84, v0
	v_mov_b32_e32 v85, v0
	v_mov_b32_e32 v86, v0
	v_mov_b32_e32 v87, v0
	v_mov_b32_e32 v64, v0
	v_mov_b32_e32 v65, v0
	v_mov_b32_e32 v66, v0
	v_mov_b32_e32 v67, v0
	v_mov_b32_e32 v60, v0
	v_mov_b32_e32 v61, v0
	v_mov_b32_e32 v62, v0
	v_mov_b32_e32 v63, v0
	v_mov_b32_e32 v80, v0
	v_mov_b32_e32 v81, v0
	v_mov_b32_e32 v82, v0
	v_mov_b32_e32 v83, v0
	v_mov_b32_e32 v76, v0
	v_mov_b32_e32 v77, v0
	v_mov_b32_e32 v78, v0
	v_mov_b32_e32 v79, v0
	v_mov_b32_e32 v92, v0
	v_mov_b32_e32 v93, v0
	v_mov_b32_e32 v94, v0
	v_mov_b32_e32 v95, v0
	v_mov_b32_e32 v88, v0
	v_mov_b32_e32 v89, v0
	v_mov_b32_e32 v90, v0
	v_mov_b32_e32 v91, v0
	s_branch .LBB0_925
.LBB0_925:
	s_and_b64 vcc, exec, s[4:5]
	s_cbranch_vccnz .Lq3_p6_one
	.p2align 7
.Lq3_p6_two:
	ds_read_b128 v[96:99], v195
	ds_read_b128 v[100:103], v195 offset:1024
	ds_read_b128 v[104:107], v195 offset:2048
	ds_read_b128 v[108:111], v195 offset:3072
	s_add_i32 m0, s39, 0xc000
	ds_read_b128 v[144:147], v196
	ds_read_b128 v[148:151], v196 offset:1024
	ds_read_b128 v[136:139], v196 offset:2048
	global_load_lds_dwordx4 v166, s[8:9]
	s_add_i32 m0, s39, 0xe000
	ds_read_b128 v[140:143], v196 offset:3072
	ds_read_b128 v[128:131], v196 offset:4096
	ds_read_b128 v[132:135], v196 offset:5120
	global_load_lds_dwordx4 v168, s[8:9]
	s_add_u32 s34, s8, 0xfffa0080
	s_addc_u32 s35, s9, -1
	s_cmp_eq_u32 s82, 28
	s_cselect_b32 s57, s49, s35
	s_cselect_b32 s56, s48, s34
	s_cselect_b32 s55, s17, s53
	s_cselect_b32 s54, s16, s52
	s_waitcnt lgkmcnt(8)
	s_barrier
	s_waitcnt lgkmcnt(0)
	v_mfma_f32_16x16x32_bf16 v[88:91], v[96:99], v[144:147], v[88:91]
	v_mfma_f32_16x16x32_bf16 v[92:95], v[104:107], v[144:147], v[92:95]
	v_mfma_f32_16x16x32_bf16 v[76:79], v[96:99], v[136:139], v[76:79]
	v_mfma_f32_16x16x32_bf16 v[80:83], v[104:107], v[136:139], v[80:83]
	v_mfma_f32_16x16x32_bf16 v[60:63], v[96:99], v[128:131], v[60:63]
	v_mfma_f32_16x16x32_bf16 v[64:67], v[104:107], v[128:131], v[64:67]
	v_mfma_f32_16x16x32_bf16 v[88:91], v[100:103], v[148:151], v[88:91]
	v_mfma_f32_16x16x32_bf16 v[92:95], v[108:111], v[148:151], v[92:95]
	v_mfma_f32_16x16x32_bf16 v[76:79], v[100:103], v[140:143], v[76:79]
	v_mfma_f32_16x16x32_bf16 v[80:83], v[108:111], v[140:143], v[80:83]
	v_mfma_f32_16x16x32_bf16 v[60:63], v[100:103], v[132:135], v[60:63]
	v_mfma_f32_16x16x32_bf16 v[64:67], v[108:111], v[132:135], v[64:67]
	s_barrier
	v_add_u32_e32 v124, 0x14000, v194
	s_mov_b32 m0, s40
	ds_read_b128 v[112:115], v124
	ds_read_b128 v[116:119], v124 offset:1024
	global_load_lds_dwordx4 v152, s[54:55]
	s_mov_b32 m0, s41
	ds_read_b128 v[120:123], v124 offset:2048
	ds_read_b128 v[124:127], v124 offset:3072
	global_load_lds_dwordx4 v154, s[54:55]
	s_barrier
	s_waitcnt lgkmcnt(0)
	v_mfma_f32_16x16x32_bf16 v[84:87], v[112:115], v[144:147], v[84:87]
	v_mfma_f32_16x16x32_bf16 v[68:71], v[120:123], v[144:147], v[68:71]
	v_mfma_f32_16x16x32_bf16 v[72:75], v[112:115], v[136:139], v[72:75]
	v_mfma_f32_16x16x32_bf16 v[52:55], v[120:123], v[136:139], v[52:55]
	v_mfma_f32_16x16x32_bf16 v[56:59], v[112:115], v[128:131], v[56:59]
	v_mfma_f32_16x16x32_bf16 v[36:39], v[120:123], v[128:131], v[36:39]
	v_mfma_f32_16x16x32_bf16 v[84:87], v[116:119], v[148:151], v[84:87]
	v_mfma_f32_16x16x32_bf16 v[68:71], v[124:127], v[148:151], v[68:71]
	v_mfma_f32_16x16x32_bf16 v[72:75], v[116:119], v[140:143], v[72:75]
	v_mfma_f32_16x16x32_bf16 v[52:55], v[124:127], v[140:143], v[52:55]
	v_mfma_f32_16x16x32_bf16 v[56:59], v[116:119], v[132:135], v[56:59]
	v_mfma_f32_16x16x32_bf16 v[36:39], v[124:127], v[132:135], v[36:39]
	s_barrier
	s_mov_b32 m0, s39
	ds_read_b128 v[144:147], v196 offset:16384
	ds_read_b128 v[148:151], v196 offset:17408
	ds_read_b128 v[136:139], v196 offset:18432
	global_load_lds_dwordx4 v152, s[56:57]
	s_add_i32 m0, s39, 0x2000
	ds_read_b128 v[140:143], v196 offset:19456
	ds_read_b128 v[128:131], v196 offset:20480
	ds_read_b128 v[132:135], v196 offset:21504
	global_load_lds_dwordx4 v154, s[56:57]
	s_barrier
	s_waitcnt lgkmcnt(0)
	v_mfma_f32_16x16x32_bf16 v[44:47], v[96:99], v[144:147], v[44:47]
	v_mfma_f32_16x16x32_bf16 v[48:51], v[104:107], v[144:147], v[48:51]
	v_mfma_f32_16x16x32_bf16 v[28:31], v[96:99], v[136:139], v[28:31]
	v_mfma_f32_16x16x32_bf16 v[32:35], v[104:107], v[136:139], v[32:35]
	v_mfma_f32_16x16x32_bf16 v[12:15], v[96:99], v[128:131], v[12:15]
	v_mfma_f32_16x16x32_bf16 v[8:11], v[104:107], v[128:131], v[8:11]
	v_mfma_f32_16x16x32_bf16 v[44:47], v[100:103], v[148:151], v[44:47]
	v_mfma_f32_16x16x32_bf16 v[48:51], v[108:111], v[148:151], v[48:51]
	v_mfma_f32_16x16x32_bf16 v[28:31], v[100:103], v[140:143], v[28:31]
	v_mfma_f32_16x16x32_bf16 v[32:35], v[108:111], v[140:143], v[32:35]
	v_mfma_f32_16x16x32_bf16 v[12:15], v[100:103], v[132:135], v[12:15]
	v_mfma_f32_16x16x32_bf16 v[8:11], v[108:111], v[132:135], v[8:11]
	s_barrier
	s_add_u32 s34, s54, 0x80000
	s_addc_u32 s35, s55, 0
	s_mov_b32 m0, s60
	s_nop 0
	global_load_lds_dwordx4 v152, s[34:35]
	s_mov_b32 m0, s61
	s_nop 0
	global_load_lds_dwordx4 v154, s[34:35]
	s_waitcnt vmcnt(6)
	s_barrier
	v_mfma_f32_16x16x32_bf16 v[40:43], v[112:115], v[144:147], v[40:43]
	v_mfma_f32_16x16x32_bf16 v[20:23], v[120:123], v[144:147], v[20:23]
	v_mfma_f32_16x16x32_bf16 v[24:27], v[112:115], v[136:139], v[24:27]
	v_mfma_f32_16x16x32_bf16 v[16:19], v[120:123], v[136:139], v[16:19]
	v_mfma_f32_16x16x32_bf16 v[4:7], v[112:115], v[128:131], v[4:7]
	v_mfma_f32_16x16x32_bf16 v[0:3], v[120:123], v[128:131], v[0:3]
	v_mfma_f32_16x16x32_bf16 v[40:43], v[116:119], v[148:151], v[40:43]
	v_mfma_f32_16x16x32_bf16 v[20:23], v[124:127], v[148:151], v[20:23]
	v_mfma_f32_16x16x32_bf16 v[24:27], v[116:119], v[140:143], v[24:27]
	v_mfma_f32_16x16x32_bf16 v[16:19], v[124:127], v[140:143], v[16:19]
	v_mfma_f32_16x16x32_bf16 v[4:7], v[116:119], v[132:135], v[4:7]
	v_mfma_f32_16x16x32_bf16 v[0:3], v[124:127], v[132:135], v[0:3]
	s_barrier
	v_add_u32_e32 v96, 0x18000, v194
	ds_read_b128 v[112:115], v96
	ds_read_b128 v[116:119], v96 offset:1024
	ds_read_b128 v[120:123], v96 offset:2048
	ds_read_b128 v[124:127], v96 offset:3072
	s_add_u32 s56, s56, 0x60000
	s_addc_u32 s57, s57, 0
	s_mov_b32 m0, s62
	ds_read_b128 v[144:147], v196 offset:32768
	ds_read_b128 v[148:151], v196 offset:33792
	ds_read_b128 v[136:139], v196 offset:34816
	global_load_lds_dwordx4 v152, s[56:57]
	s_add_i32 m0, s39, 0x6000
	ds_read_b128 v[140:143], v196 offset:35840
	ds_read_b128 v[128:131], v196 offset:36864
	ds_read_b128 v[132:135], v196 offset:37888
	global_load_lds_dwordx4 v154, s[56:57]
	s_waitcnt lgkmcnt(8)
	s_barrier
	s_waitcnt lgkmcnt(0)
	v_mfma_f32_16x16x32_bf16 v[88:91], v[112:115], v[144:147], v[88:91]
	v_mfma_f32_16x16x32_bf16 v[92:95], v[120:123], v[144:147], v[92:95]
	v_mfma_f32_16x16x32_bf16 v[76:79], v[112:115], v[136:139], v[76:79]
	v_mfma_f32_16x16x32_bf16 v[80:83], v[120:123], v[136:139], v[80:83]
	v_mfma_f32_16x16x32_bf16 v[60:63], v[112:115], v[128:131], v[60:63]
	v_mfma_f32_16x16x32_bf16 v[64:67], v[120:123], v[128:131], v[64:67]
	v_mfma_f32_16x16x32_bf16 v[88:91], v[116:119], v[148:151], v[88:91]
	v_mfma_f32_16x16x32_bf16 v[92:95], v[124:127], v[148:151], v[92:95]
	v_mfma_f32_16x16x32_bf16 v[76:79], v[116:119], v[140:143], v[76:79]
	v_mfma_f32_16x16x32_bf16 v[80:83], v[124:127], v[140:143], v[80:83]
	v_mfma_f32_16x16x32_bf16 v[60:63], v[116:119], v[132:135], v[60:63]
	v_mfma_f32_16x16x32_bf16 v[64:67], v[124:127], v[132:135], v[64:67]
	s_barrier
	v_add_u32_e32 v108, 0x1c000, v194
	s_add_u32 s34, s54, 0x80
	s_addc_u32 s35, s55, 0
	s_mov_b32 m0, s63
	ds_read_b128 v[96:99], v108
	ds_read_b128 v[100:103], v108 offset:1024
	global_load_lds_dwordx4 v152, s[34:35]
	s_mov_b32 m0, s64
	ds_read_b128 v[104:107], v108 offset:2048
	ds_read_b128 v[108:111], v108 offset:3072
	global_load_lds_dwordx4 v154, s[34:35]
	s_barrier
	s_waitcnt lgkmcnt(0)
	v_mfma_f32_16x16x32_bf16 v[84:87], v[96:99], v[144:147], v[84:87]
	v_mfma_f32_16x16x32_bf16 v[68:71], v[104:107], v[144:147], v[68:71]
	v_mfma_f32_16x16x32_bf16 v[72:75], v[96:99], v[136:139], v[72:75]
	v_mfma_f32_16x16x32_bf16 v[52:55], v[104:107], v[136:139], v[52:55]
	v_mfma_f32_16x16x32_bf16 v[56:59], v[96:99], v[128:131], v[56:59]
	v_mfma_f32_16x16x32_bf16 v[36:39], v[104:107], v[128:131], v[36:39]
	v_mfma_f32_16x16x32_bf16 v[84:87], v[100:103], v[148:151], v[84:87]
	v_mfma_f32_16x16x32_bf16 v[68:71], v[108:111], v[148:151], v[68:71]
	v_mfma_f32_16x16x32_bf16 v[72:75], v[100:103], v[140:143], v[72:75]
	v_mfma_f32_16x16x32_bf16 v[52:55], v[108:111], v[140:143], v[52:55]
	v_mfma_f32_16x16x32_bf16 v[56:59], v[100:103], v[132:135], v[56:59]
	v_mfma_f32_16x16x32_bf16 v[36:39], v[108:111], v[132:135], v[36:39]
	s_barrier
	s_add_u32 s34, s56, 0xfffa0080
	s_addc_u32 s35, s57, -1
	s_mov_b32 m0, s65
	ds_read_b128 v[144:147], v196 offset:49152
	ds_read_b128 v[148:151], v196 offset:50176
	ds_read_b128 v[136:139], v196 offset:51200
	global_load_lds_dwordx4 v152, s[34:35]
	s_add_i32 m0, s39, 0xa000
	ds_read_b128 v[140:143], v196 offset:52224
	ds_read_b128 v[128:131], v196 offset:53248
	ds_read_b128 v[132:135], v196 offset:54272
	global_load_lds_dwordx4 v154, s[34:35]
	s_barrier
	s_waitcnt lgkmcnt(0)
	v_mfma_f32_16x16x32_bf16 v[44:47], v[112:115], v[144:147], v[44:47]
	v_mfma_f32_16x16x32_bf16 v[48:51], v[120:123], v[144:147], v[48:51]
	v_mfma_f32_16x16x32_bf16 v[28:31], v[112:115], v[136:139], v[28:31]
	v_mfma_f32_16x16x32_bf16 v[32:35], v[120:123], v[136:139], v[32:35]
	v_mfma_f32_16x16x32_bf16 v[12:15], v[112:115], v[128:131], v[12:15]
	v_mfma_f32_16x16x32_bf16 v[8:11], v[120:123], v[128:131], v[8:11]
	v_mfma_f32_16x16x32_bf16 v[44:47], v[116:119], v[148:151], v[44:47]
	v_mfma_f32_16x16x32_bf16 v[48:51], v[124:127], v[148:151], v[48:51]
	v_mfma_f32_16x16x32_bf16 v[28:31], v[116:119], v[140:143], v[28:31]
	v_mfma_f32_16x16x32_bf16 v[32:35], v[124:127], v[140:143], v[32:35]
	v_mfma_f32_16x16x32_bf16 v[12:15], v[116:119], v[132:135], v[12:15]
	v_mfma_f32_16x16x32_bf16 v[8:11], v[124:127], v[132:135], v[8:11]
	s_barrier
	s_add_u32 s34, s54, 0x80080
	s_addc_u32 s35, s55, 0
	s_mov_b32 m0, s66
	s_add_i32 s82, s82, 2
	global_load_lds_dwordx4 v152, s[34:35]
	s_mov_b32 m0, s67
	s_nop 0
	global_load_lds_dwordx4 v154, s[34:35]
	s_add_u32 s8, s8, 0x100
	s_addc_u32 s9, s9, 0
	s_add_u32 s52, s52, 0x100
	s_addc_u32 s53, s53, 0
	s_waitcnt vmcnt(6)
	s_barrier
	v_mfma_f32_16x16x32_bf16 v[40:43], v[96:99], v[144:147], v[40:43]
	v_mfma_f32_16x16x32_bf16 v[20:23], v[104:107], v[144:147], v[20:23]
	v_mfma_f32_16x16x32_bf16 v[24:27], v[96:99], v[136:139], v[24:27]
	v_mfma_f32_16x16x32_bf16 v[16:19], v[104:107], v[136:139], v[16:19]
	v_mfma_f32_16x16x32_bf16 v[4:7], v[96:99], v[128:131], v[4:7]
	v_mfma_f32_16x16x32_bf16 v[0:3], v[104:107], v[128:131], v[0:3]
	v_mfma_f32_16x16x32_bf16 v[40:43], v[100:103], v[148:151], v[40:43]
	v_mfma_f32_16x16x32_bf16 v[20:23], v[108:111], v[148:151], v[20:23]
	v_mfma_f32_16x16x32_bf16 v[24:27], v[100:103], v[140:143], v[24:27]
	v_mfma_f32_16x16x32_bf16 v[16:19], v[108:111], v[140:143], v[16:19]
	v_mfma_f32_16x16x32_bf16 v[4:7], v[100:103], v[132:135], v[4:7]
	v_mfma_f32_16x16x32_bf16 v[0:3], v[108:111], v[132:135], v[0:3]
	s_cmp_gt_u32 s82, 29
	s_barrier
	s_cbranch_scc0 .Lq3_p6_two
	s_branch .LBB0_941
	.p2align 7
.Lq3_p6_one:
	ds_read_b128 v[96:99], v195
	ds_read_b128 v[100:103], v195 offset:1024
	ds_read_b128 v[104:107], v195 offset:2048
	ds_read_b128 v[108:111], v195 offset:3072
	s_add_i32 m0, s39, 0xc000
	ds_read_b128 v[144:147], v196
	ds_read_b128 v[148:151], v196 offset:1024
	ds_read_b128 v[136:139], v196 offset:2048
	global_load_lds_dwordx4 v166, s[8:9]
	ds_read_b128 v[140:143], v196 offset:3072
	ds_read_b128 v[128:131], v196 offset:4096
	ds_read_b128 v[132:135], v196 offset:5120
	s_add_u32 s34, s8, 0xfffa0080
	s_addc_u32 s35, s9, -1
	s_cmp_eq_u32 s82, 28
	s_cselect_b32 s57, s49, s35
	s_cselect_b32 s56, s48, s34
	s_cselect_b32 s55, s17, s53
	s_cselect_b32 s54, s16, s52
	s_waitcnt lgkmcnt(8)
	s_barrier
	s_waitcnt lgkmcnt(0)
	v_mfma_f32_16x16x32_bf16 v[88:91], v[96:99], v[144:147], v[88:91]
	v_mfma_f32_16x16x32_bf16 v[92:95], v[104:107], v[144:147], v[92:95]
	v_mfma_f32_16x16x32_bf16 v[76:79], v[96:99], v[136:139], v[76:79]
	v_mfma_f32_16x16x32_bf16 v[80:83], v[104:107], v[136:139], v[80:83]
	v_mfma_f32_16x16x32_bf16 v[60:63], v[96:99], v[128:131], v[60:63]
	v_mfma_f32_16x16x32_bf16 v[64:67], v[104:107], v[128:131], v[64:67]
	v_mfma_f32_16x16x32_bf16 v[88:91], v[100:103], v[148:151], v[88:91]
	v_mfma_f32_16x16x32_bf16 v[92:95], v[108:111], v[148:151], v[92:95]
	v_mfma_f32_16x16x32_bf16 v[76:79], v[100:103], v[140:143], v[76:79]
	v_mfma_f32_16x16x32_bf16 v[80:83], v[108:111], v[140:143], v[80:83]
	v_mfma_f32_16x16x32_bf16 v[60:63], v[100:103], v[132:135], v[60:63]
	v_mfma_f32_16x16x32_bf16 v[64:67], v[108:111], v[132:135], v[64:67]
	s_barrier
	v_add_u32_e32 v124, 0x14000, v194
	s_mov_b32 m0, s40
	ds_read_b128 v[112:115], v124
	ds_read_b128 v[116:119], v124 offset:1024
	global_load_lds_dwordx4 v152, s[54:55]
	s_mov_b32 m0, s41
	ds_read_b128 v[120:123], v124 offset:2048
	ds_read_b128 v[124:127], v124 offset:3072
	global_load_lds_dwordx4 v154, s[54:55]
	s_barrier
	s_waitcnt lgkmcnt(0)
	v_mfma_f32_16x16x32_bf16 v[84:87], v[112:115], v[144:147], v[84:87]
	v_mfma_f32_16x16x32_bf16 v[68:71], v[120:123], v[144:147], v[68:71]
	v_mfma_f32_16x16x32_bf16 v[72:75], v[112:115], v[136:139], v[72:75]
	v_mfma_f32_16x16x32_bf16 v[52:55], v[120:123], v[136:139], v[52:55]
	v_mfma_f32_16x16x32_bf16 v[56:59], v[112:115], v[128:131], v[56:59]
	v_mfma_f32_16x16x32_bf16 v[36:39], v[120:123], v[128:131], v[36:39]
	v_mfma_f32_16x16x32_bf16 v[84:87], v[116:119], v[148:151], v[84:87]
	v_mfma_f32_16x16x32_bf16 v[68:71], v[124:127], v[148:151], v[68:71]
	v_mfma_f32_16x16x32_bf16 v[72:75], v[116:119], v[140:143], v[72:75]
	v_mfma_f32_16x16x32_bf16 v[52:55], v[124:127], v[140:143], v[52:55]
	v_mfma_f32_16x16x32_bf16 v[56:59], v[116:119], v[132:135], v[56:59]
	v_mfma_f32_16x16x32_bf16 v[36:39], v[124:127], v[132:135], v[36:39]
	s_barrier
	s_mov_b32 m0, s39
	ds_read_b128 v[144:147], v196 offset:16384
	ds_read_b128 v[148:151], v196 offset:17408
	ds_read_b128 v[136:139], v196 offset:18432
	global_load_lds_dwordx4 v152, s[56:57]
	ds_read_b128 v[140:143], v196 offset:19456
	ds_read_b128 v[128:131], v196 offset:20480
	ds_read_b128 v[132:135], v196 offset:21504
	s_barrier
	s_waitcnt lgkmcnt(0)
	v_mfma_f32_16x16x32_bf16 v[44:47], v[96:99], v[144:147], v[44:47]
	v_mfma_f32_16x16x32_bf16 v[48:51], v[104:107], v[144:147], v[48:51]
	v_mfma_f32_16x16x32_bf16 v[28:31], v[96:99], v[136:139], v[28:31]
	v_mfma_f32_16x16x32_bf16 v[32:35], v[104:107], v[136:139], v[32:35]
	v_mfma_f32_16x16x32_bf16 v[12:15], v[96:99], v[128:131], v[12:15]
	v_mfma_f32_16x16x32_bf16 v[8:11], v[104:107], v[128:131], v[8:11]
	v_mfma_f32_16x16x32_bf16 v[44:47], v[100:103], v[148:151], v[44:47]
	v_mfma_f32_16x16x32_bf16 v[48:51], v[108:111], v[148:151], v[48:51]
	v_mfma_f32_16x16x32_bf16 v[28:31], v[100:103], v[140:143], v[28:31]
	v_mfma_f32_16x16x32_bf16 v[32:35], v[108:111], v[140:143], v[32:35]
	v_mfma_f32_16x16x32_bf16 v[12:15], v[100:103], v[132:135], v[12:15]
	v_mfma_f32_16x16x32_bf16 v[8:11], v[108:111], v[132:135], v[8:11]
	s_barrier
	s_add_u32 s34, s54, 0x80000
	s_addc_u32 s35, s55, 0
	s_mov_b32 m0, s60
	s_nop 0
	global_load_lds_dwordx4 v152, s[34:35]
	s_mov_b32 m0, s61
	s_nop 0
	global_load_lds_dwordx4 v154, s[34:35]
	s_waitcnt vmcnt(5)
	s_barrier
	v_mfma_f32_16x16x32_bf16 v[40:43], v[112:115], v[144:147], v[40:43]
	v_mfma_f32_16x16x32_bf16 v[20:23], v[120:123], v[144:147], v[20:23]
	v_mfma_f32_16x16x32_bf16 v[24:27], v[112:115], v[136:139], v[24:27]
	v_mfma_f32_16x16x32_bf16 v[16:19], v[120:123], v[136:139], v[16:19]
	v_mfma_f32_16x16x32_bf16 v[4:7], v[112:115], v[128:131], v[4:7]
	v_mfma_f32_16x16x32_bf16 v[0:3], v[120:123], v[128:131], v[0:3]
	v_mfma_f32_16x16x32_bf16 v[40:43], v[116:119], v[148:151], v[40:43]
	v_mfma_f32_16x16x32_bf16 v[20:23], v[124:127], v[148:151], v[20:23]
	v_mfma_f32_16x16x32_bf16 v[24:27], v[116:119], v[140:143], v[24:27]
	v_mfma_f32_16x16x32_bf16 v[16:19], v[124:127], v[140:143], v[16:19]
	v_mfma_f32_16x16x32_bf16 v[4:7], v[116:119], v[132:135], v[4:7]
	v_mfma_f32_16x16x32_bf16 v[0:3], v[124:127], v[132:135], v[0:3]
	s_barrier
	v_add_u32_e32 v96, 0x18000, v194
	ds_read_b128 v[112:115], v96
	ds_read_b128 v[116:119], v96 offset:1024
	ds_read_b128 v[120:123], v96 offset:2048
	ds_read_b128 v[124:127], v96 offset:3072
	s_add_u32 s56, s56, 0x60000
	s_addc_u32 s57, s57, 0
	s_mov_b32 m0, s62
	ds_read_b128 v[144:147], v196 offset:32768
	ds_read_b128 v[148:151], v196 offset:33792
	ds_read_b128 v[136:139], v196 offset:34816
	global_load_lds_dwordx4 v152, s[56:57]
	ds_read_b128 v[140:143], v196 offset:35840
	ds_read_b128 v[128:131], v196 offset:36864
	ds_read_b128 v[132:135], v196 offset:37888
	s_waitcnt lgkmcnt(8)
	s_barrier
	s_waitcnt lgkmcnt(0)
	v_mfma_f32_16x16x32_bf16 v[88:91], v[112:115], v[144:147], v[88:91]
	v_mfma_f32_16x16x32_bf16 v[92:95], v[120:123], v[144:147], v[92:95]
	v_mfma_f32_16x16x32_bf16 v[76:79], v[112:115], v[136:139], v[76:79]
	v_mfma_f32_16x16x32_bf16 v[80:83], v[120:123], v[136:139], v[80:83]
	v_mfma_f32_16x16x32_bf16 v[60:63], v[112:115], v[128:131], v[60:63]
	v_mfma_f32_16x16x32_bf16 v[64:67], v[120:123], v[128:131], v[64:67]
	v_mfma_f32_16x16x32_bf16 v[88:91], v[116:119], v[148:151], v[88:91]
	v_mfma_f32_16x16x32_bf16 v[92:95], v[124:127], v[148:151], v[92:95]
	v_mfma_f32_16x16x32_bf16 v[76:79], v[116:119], v[140:143], v[76:79]
	v_mfma_f32_16x16x32_bf16 v[80:83], v[124:127], v[140:143], v[80:83]
	v_mfma_f32_16x16x32_bf16 v[60:63], v[116:119], v[132:135], v[60:63]
	v_mfma_f32_16x16x32_bf16 v[64:67], v[124:127], v[132:135], v[64:67]
	s_barrier
	v_add_u32_e32 v108, 0x1c000, v194
	s_add_u32 s34, s54, 0x80
	s_addc_u32 s35, s55, 0
	s_mov_b32 m0, s63
	ds_read_b128 v[96:99], v108
	ds_read_b128 v[100:103], v108 offset:1024
	global_load_lds_dwordx4 v152, s[34:35]
	s_mov_b32 m0, s64
	ds_read_b128 v[104:107], v108 offset:2048
	ds_read_b128 v[108:111], v108 offset:3072
	global_load_lds_dwordx4 v154, s[34:35]
	s_barrier
	s_waitcnt lgkmcnt(0)
	v_mfma_f32_16x16x32_bf16 v[84:87], v[96:99], v[144:147], v[84:87]
	v_mfma_f32_16x16x32_bf16 v[68:71], v[104:107], v[144:147], v[68:71]
	v_mfma_f32_16x16x32_bf16 v[72:75], v[96:99], v[136:139], v[72:75]
	v_mfma_f32_16x16x32_bf16 v[52:55], v[104:107], v[136:139], v[52:55]
	v_mfma_f32_16x16x32_bf16 v[56:59], v[96:99], v[128:131], v[56:59]
	v_mfma_f32_16x16x32_bf16 v[36:39], v[104:107], v[128:131], v[36:39]
	v_mfma_f32_16x16x32_bf16 v[84:87], v[100:103], v[148:151], v[84:87]
	v_mfma_f32_16x16x32_bf16 v[68:71], v[108:111], v[148:151], v[68:71]
	v_mfma_f32_16x16x32_bf16 v[72:75], v[100:103], v[140:143], v[72:75]
	v_mfma_f32_16x16x32_bf16 v[52:55], v[108:111], v[140:143], v[52:55]
	v_mfma_f32_16x16x32_bf16 v[56:59], v[100:103], v[132:135], v[56:59]
	v_mfma_f32_16x16x32_bf16 v[36:39], v[108:111], v[132:135], v[36:39]
	s_barrier
	s_add_u32 s34, s56, 0xfffa0080
	s_addc_u32 s35, s57, -1
	s_mov_b32 m0, s65
	ds_read_b128 v[144:147], v196 offset:49152
	ds_read_b128 v[148:151], v196 offset:50176
	ds_read_b128 v[136:139], v196 offset:51200
	global_load_lds_dwordx4 v152, s[34:35]
	ds_read_b128 v[140:143], v196 offset:52224
	ds_read_b128 v[128:131], v196 offset:53248
	ds_read_b128 v[132:135], v196 offset:54272
	s_barrier
	s_waitcnt lgkmcnt(0)
	v_mfma_f32_16x16x32_bf16 v[44:47], v[112:115], v[144:147], v[44:47]
	v_mfma_f32_16x16x32_bf16 v[48:51], v[120:123], v[144:147], v[48:51]
	v_mfma_f32_16x16x32_bf16 v[28:31], v[112:115], v[136:139], v[28:31]
	v_mfma_f32_16x16x32_bf16 v[32:35], v[120:123], v[136:139], v[32:35]
	v_mfma_f32_16x16x32_bf16 v[12:15], v[112:115], v[128:131], v[12:15]
	v_mfma_f32_16x16x32_bf16 v[8:11], v[120:123], v[128:131], v[8:11]
	v_mfma_f32_16x16x32_bf16 v[44:47], v[116:119], v[148:151], v[44:47]
	v_mfma_f32_16x16x32_bf16 v[48:51], v[124:127], v[148:151], v[48:51]
	v_mfma_f32_16x16x32_bf16 v[28:31], v[116:119], v[140:143], v[28:31]
	v_mfma_f32_16x16x32_bf16 v[32:35], v[124:127], v[140:143], v[32:35]
	v_mfma_f32_16x16x32_bf16 v[12:15], v[116:119], v[132:135], v[12:15]
	v_mfma_f32_16x16x32_bf16 v[8:11], v[124:127], v[132:135], v[8:11]
	s_barrier
	s_add_u32 s34, s54, 0x80080
	s_addc_u32 s35, s55, 0
	s_mov_b32 m0, s66
	s_add_i32 s82, s82, 2
	global_load_lds_dwordx4 v152, s[34:35]
	s_mov_b32 m0, s67
	s_nop 0
	global_load_lds_dwordx4 v154, s[34:35]
	s_add_u32 s8, s8, 0x100
	s_addc_u32 s9, s9, 0
	s_add_u32 s52, s52, 0x100
	s_addc_u32 s53, s53, 0
	s_waitcnt vmcnt(5)
	s_barrier
	v_mfma_f32_16x16x32_bf16 v[40:43], v[96:99], v[144:147], v[40:43]
	v_mfma_f32_16x16x32_bf16 v[20:23], v[104:107], v[144:147], v[20:23]
	v_mfma_f32_16x16x32_bf16 v[24:27], v[96:99], v[136:139], v[24:27]
	v_mfma_f32_16x16x32_bf16 v[16:19], v[104:107], v[136:139], v[16:19]
	v_mfma_f32_16x16x32_bf16 v[4:7], v[96:99], v[128:131], v[4:7]
	v_mfma_f32_16x16x32_bf16 v[0:3], v[104:107], v[128:131], v[0:3]
	v_mfma_f32_16x16x32_bf16 v[40:43], v[100:103], v[148:151], v[40:43]
	v_mfma_f32_16x16x32_bf16 v[20:23], v[108:111], v[148:151], v[20:23]
	v_mfma_f32_16x16x32_bf16 v[24:27], v[100:103], v[140:143], v[24:27]
	v_mfma_f32_16x16x32_bf16 v[16:19], v[108:111], v[140:143], v[16:19]
	v_mfma_f32_16x16x32_bf16 v[4:7], v[100:103], v[132:135], v[4:7]
	v_mfma_f32_16x16x32_bf16 v[0:3], v[108:111], v[132:135], v[0:3]
	s_cmp_gt_u32 s82, 29
	s_barrier
	s_cbranch_scc0 .Lq3_p6_one
